# gemm64_ctx rolled K loops: counted vmcnt waits (set-1 loads stay in flight across loop top) instead of vmcnt(0)
# baseline (speedup 1.0000x reference)
.LBB0_815:
	s_ashr_i32 s2, s4, 31
	s_lshr_b32 s2, s2, 28
	s_add_i32 s2, s4, s2
	s_ashr_i32 s2, s2, 4
	s_lshl_b32 s3, s2, 10
	s_lshl_b32 s6, s4, 6
	s_lshl_b32 s5, s2, 6
	s_sub_i32 s6, s6, s3
	s_mul_i32 s2, s2, 0x58000
	v_readlane_b32 s7, v253, 3
	s_mul_hi_i32 s3, s5, 0x1600
	s_add_u32 s2, s7, s2
	v_readlane_b32 s7, v253, 4
	s_addc_u32 s3, s7, s3
	s_mul_i32 s10, s6, 0x1600
	v_readlane_b32 s12, v253, 44
	s_mul_hi_i32 s7, s6, 0x1600
	v_readlane_b32 s13, v253, 45
	s_add_u32 s10, s12, s10
	v_lshl_add_u64 v[0:1], s[2:3], 0, v[128:129]
	v_mov_b32_e32 v89, v129
	s_addc_u32 s11, s13, s7
	v_lshl_add_u64 v[8:9], v[0:1], 0, v[88:89]
	s_mov_b32 s7, 0x16000
	v_add_co_u32_e32 v4, vcc, s7, v8
	v_mov_b32_e32 v87, v129
	s_nop 0
	v_addc_co_u32_e32 v5, vcc, 0, v9, vcc
	s_mov_b32 s12, 0x2c000
	v_lshl_add_u64 v[2:3], s[10:11], 0, v[86:87]
	v_add_co_u32_e32 v10, vcc, s12, v8
	v_lshl_add_u64 v[2:3], v[2:3], 0, v[128:129]
	s_nop 0
	v_addc_co_u32_e32 v11, vcc, 0, v9, vcc
	s_mov_b32 s13, 0x42000
	global_load_dwordx4 v[20:23], v[2:3], off offset:256
	s_nop 0
	global_load_dwordx4 v[0:3], v[8:9], off
	s_nop 0
	global_load_dwordx4 v[4:7], v[4:5], off
	v_add_co_u32_e32 v8, vcc, s13, v8
	v_mov_b32_e32 v91, v129
	s_nop 0
	v_addc_co_u32_e32 v9, vcc, 0, v9, vcc
	global_load_dwordx4 v[16:19], v[10:11], off
	global_load_dwordx4 v[24:27], v[8:9], off
	v_lshl_add_u64 v[8:9], s[2:3], 0, v[88:89]
	v_lshl_add_u64 v[28:29], v[8:9], 0, v[128:129]
	v_add_co_u32_e32 v12, vcc, s7, v28
	v_mov_b32_e32 v93, v129
	s_nop 0
	v_addc_co_u32_e32 v13, vcc, 0, v29, vcc
	v_add_co_u32_e32 v30, vcc, s12, v28
	global_load_dwordx4 v[8:11], v[28:29], off offset:256
	s_nop 0
	global_load_dwordx4 v[12:15], v[12:13], off offset:256
	v_addc_co_u32_e32 v31, vcc, 0, v29, vcc
	v_add_co_u32_e32 v28, vcc, s13, v28
	v_lshl_add_u64 v[40:41], s[10:11], 0, v[128:129]
	s_nop 0
	v_addc_co_u32_e32 v29, vcc, 0, v29, vcc
	global_load_dwordx4 v[32:35], v[30:31], off offset:256
	global_load_dwordx4 v[44:47], v[28:29], off offset:256
	v_lshl_add_u64 v[28:29], s[10:11], 0, v[90:91]
	v_lshl_add_u64 v[28:29], v[28:29], 0, v[128:129]
	v_lshl_add_u64 v[30:31], s[10:11], 0, v[92:93]
	v_add_co_u32_e32 v54, vcc, s7, v28
	v_lshl_add_u64 v[42:43], v[30:31], 0, v[128:129]
	s_nop 0
	v_addc_co_u32_e32 v55, vcc, 0, v29, vcc
	global_load_dwordx4 v[48:51], v[28:29], off offset:256
	global_load_dwordx4 v[36:39], v[42:43], off offset:256
	v_lshl_add_u64 v[30:31], s[10:11], 0, v[88:89]
	v_add_co_u32_e32 v42, vcc, s7, v42
	v_lshl_add_u64 v[52:53], v[30:31], 0, v[128:129]
	s_nop 0
	v_addc_co_u32_e32 v43, vcc, 0, v43, vcc
	global_load_dwordx4 v[28:31], v[52:53], off offset:256
	global_load_dwordx4 v[60:63], v[54:55], off
	v_add_co_u32_e32 v52, vcc, s7, v52
	v_lshl_add_u64 v[40:41], v[40:41], 0, v[88:89]
	s_nop 0
	v_addc_co_u32_e32 v53, vcc, 0, v53, vcc
	global_load_dwordx4 v[56:59], v[42:43], off
	s_nop 0
	global_load_dwordx4 v[52:55], v[52:53], off
	v_mov_b32_e32 v64, 0
	global_load_dwordx4 v[40:43], v[40:41], off
	v_mad_i64_i32 v[94:95], s[2:3], s6, v190, v[82:83]
	v_mad_i64_i32 v[96:97], s[2:3], s5, v190, v[84:85]
	s_mov_b32 s7, -2
	v_mov_b32_e32 v65, v64
	v_mov_b32_e32 v66, v64
	v_mov_b32_e32 v67, v64
	v_mov_b32_e32 v68, v64
	v_mov_b32_e32 v69, v64
	v_mov_b32_e32 v70, v64
	v_mov_b32_e32 v71, v64
	v_mov_b32_e32 v72, v64
	v_mov_b32_e32 v73, v64
	v_mov_b32_e32 v74, v64
	v_mov_b32_e32 v75, v64
	v_mov_b32_e32 v76, v64
	v_mov_b32_e32 v77, v64
	v_mov_b32_e32 v78, v64
	v_mov_b32_e32 v79, v64
	s_mov_b64 s[10:11], 0x200
	s_waitcnt vmcnt(0)
	s_branch .LBB0_817

.LBB0_817:
	s_add_i32 s7, s7, 2
	s_cmp_gt_u32 s7, 19
	s_cselect_b64 s[2:3], -1, 0
	s_and_b64 vcc, exec, s[2:3]
	s_waitcnt lgkmcnt(0)
	s_barrier
	s_waitcnt vmcnt(8)
	ds_write_b128 v100, v[0:3]
	ds_write_b128 v100, v[40:43] offset:17408
	ds_write_b128 v101, v[4:7]
	ds_write_b128 v101, v[52:55] offset:17408
	ds_write_b128 v102, v[16:19]
	ds_write_b128 v102, v[56:59] offset:17408
	ds_write_b128 v103, v[24:27]
	ds_write_b128 v103, v[60:63] offset:17408
	s_waitcnt lgkmcnt(0)
	s_barrier
	s_cbranch_vccnz .LBB0_819
	v_lshl_add_u64 v[24:25], v[96:97], 0, v[80:81]
	v_add_co_u32_e32 v0, vcc, 0xb000000, v24
	v_lshl_add_u64 v[60:61], v[94:95], 0, v[80:81]
	s_nop 0
	v_addc_co_u32_e32 v1, vcc, 0, v25, vcc
	v_add_co_u32_e32 v4, vcc, 0xb00000, v60
	global_load_dwordx4 v[0:3], v[0:1], off offset:512
	s_nop 0
	v_addc_co_u32_e32 v5, vcc, 0, v61, vcc
	global_load_dwordx4 v[40:43], v[4:5], off offset:512
	v_add_co_u32_e32 v4, vcc, 0xb016000, v24
	s_nop 1
	v_addc_co_u32_e32 v5, vcc, 0, v25, vcc
	v_add_co_u32_e32 v16, vcc, 0xb16000, v60
	global_load_dwordx4 v[4:7], v[4:5], off offset:512
	s_nop 0
	v_addc_co_u32_e32 v17, vcc, 0, v61, vcc
	global_load_dwordx4 v[52:55], v[16:17], off offset:512
	v_add_co_u32_e32 v16, vcc, 0xb02c000, v24
	s_nop 1
	v_addc_co_u32_e32 v17, vcc, 0, v25, vcc
	v_add_co_u32_e32 v26, vcc, 0xb2c000, v60
	global_load_dwordx4 v[16:19], v[16:17], off offset:512
	s_nop 0
	v_addc_co_u32_e32 v27, vcc, 0, v61, vcc
	v_add_co_u32_e32 v24, vcc, 0xb042000, v24
	global_load_dwordx4 v[56:59], v[26:27], off offset:512
	s_nop 0
	v_addc_co_u32_e32 v25, vcc, 0, v25, vcc
	v_add_co_u32_e32 v60, vcc, 0xb42000, v60
	s_nop 1
	v_addc_co_u32_e32 v61, vcc, 0, v61, vcc
	global_load_dwordx4 v[60:63], v[60:61], off offset:512
	s_nop 0
	global_load_dwordx4 v[24:27], v[24:25], off offset:512
.LBB0_819:
	ds_read_b128 v[106:109], v104
	ds_read_b128 v[110:113], v104 offset:4352
	ds_read_b128 v[114:117], v105 offset:17408
	ds_read_b128 v[118:121], v105 offset:21760
	s_cmp_gt_u32 s7, 18
	s_waitcnt lgkmcnt(1)
	v_mfma_f32_16x16x32_bf16 v[76:79], v[114:117], v[106:109], v[76:79]
	s_waitcnt lgkmcnt(0)
	v_mfma_f32_16x16x32_bf16 v[72:75], v[118:121], v[106:109], v[72:75]
	v_mfma_f32_16x16x32_bf16 v[68:71], v[114:117], v[110:113], v[68:71]
	v_mfma_f32_16x16x32_bf16 v[64:67], v[118:121], v[110:113], v[64:67]
	ds_read_b128 v[106:109], v104 offset:64
	ds_read_b128 v[110:113], v104 offset:4416
	ds_read_b128 v[114:117], v105 offset:17472
	ds_read_b128 v[118:121], v105 offset:21824
	s_waitcnt lgkmcnt(1)
	v_mfma_f32_16x16x32_bf16 v[76:79], v[114:117], v[106:109], v[76:79]
	s_waitcnt lgkmcnt(0)
	v_mfma_f32_16x16x32_bf16 v[72:75], v[118:121], v[106:109], v[72:75]
	v_mfma_f32_16x16x32_bf16 v[68:71], v[114:117], v[110:113], v[68:71]
	v_mfma_f32_16x16x32_bf16 v[64:67], v[118:121], v[110:113], v[64:67]
	ds_read_b128 v[106:109], v104 offset:128
	ds_read_b128 v[110:113], v104 offset:4480
	ds_read_b128 v[114:117], v105 offset:17536
	ds_read_b128 v[118:121], v105 offset:21888
	s_waitcnt lgkmcnt(1)
	v_mfma_f32_16x16x32_bf16 v[76:79], v[114:117], v[106:109], v[76:79]
	s_waitcnt lgkmcnt(0)
	v_mfma_f32_16x16x32_bf16 v[72:75], v[118:121], v[106:109], v[72:75]
	v_mfma_f32_16x16x32_bf16 v[68:71], v[114:117], v[110:113], v[68:71]
	v_mfma_f32_16x16x32_bf16 v[64:67], v[118:121], v[110:113], v[64:67]
	ds_read_b128 v[106:109], v104 offset:192
	ds_read_b128 v[110:113], v104 offset:4544
	ds_read_b128 v[114:117], v105 offset:17600
	ds_read_b128 v[118:121], v105 offset:21952
	s_waitcnt lgkmcnt(0)
	s_barrier
	v_mfma_f32_16x16x32_bf16 v[76:79], v[114:117], v[106:109], v[76:79]
	s_waitcnt vmcnt(8)
	s_cbranch_scc0 .Lg64w0
	s_waitcnt vmcnt(0)
.Lg64w0:
	ds_write_b128 v100, v[8:11]
	ds_write_b128 v100, v[28:31] offset:17408
	ds_write_b128 v101, v[12:15]
	ds_write_b128 v101, v[36:39] offset:17408
	ds_write_b128 v102, v[32:35]
	ds_write_b128 v102, v[48:51] offset:17408
	ds_write_b128 v103, v[44:47]
	ds_write_b128 v103, v[20:23] offset:17408
	s_waitcnt lgkmcnt(0)
	v_mfma_f32_16x16x32_bf16 v[72:75], v[118:121], v[106:109], v[72:75]
	s_barrier
	v_mfma_f32_16x16x32_bf16 v[68:71], v[114:117], v[110:113], v[68:71]
	v_mfma_f32_16x16x32_bf16 v[64:67], v[118:121], v[110:113], v[64:67]
	s_cbranch_scc1 .LBB0_816
	v_lshl_add_u64 v[20:21], v[96:97], 0, v[80:81]
	v_add_co_u32_e32 v8, vcc, 0xb000000, v20
	v_lshl_add_u64 v[22:23], v[94:95], 0, v[80:81]
	s_nop 0
	v_addc_co_u32_e32 v9, vcc, 0, v21, vcc
	v_add_co_u32_e32 v12, vcc, 0xb00000, v22
	global_load_dwordx4 v[8:11], v[8:9], off offset:768
	s_nop 0
	v_addc_co_u32_e32 v13, vcc, 0, v23, vcc
	global_load_dwordx4 v[28:31], v[12:13], off offset:768
	v_add_co_u32_e32 v12, vcc, 0xb016000, v20
	s_nop 1
	v_addc_co_u32_e32 v13, vcc, 0, v21, vcc
	v_add_co_u32_e32 v32, vcc, 0xb16000, v22
	global_load_dwordx4 v[12:15], v[12:13], off offset:768
	s_nop 0
	v_addc_co_u32_e32 v33, vcc, 0, v23, vcc
	global_load_dwordx4 v[36:39], v[32:33], off offset:768
	v_add_co_u32_e32 v32, vcc, 0xb02c000, v20
	s_nop 1
	v_addc_co_u32_e32 v33, vcc, 0, v21, vcc
	v_add_co_u32_e32 v44, vcc, 0xb2c000, v22
	global_load_dwordx4 v[32:35], v[32:33], off offset:768
	s_nop 0
	v_addc_co_u32_e32 v45, vcc, 0, v23, vcc
	v_add_co_u32_e32 v20, vcc, 0xb042000, v20
	global_load_dwordx4 v[48:51], v[44:45], off offset:768
	s_nop 0
	v_addc_co_u32_e32 v21, vcc, 0, v21, vcc
	global_load_dwordx4 v[44:47], v[20:21], off offset:768
	v_add_co_u32_e32 v20, vcc, 0xb42000, v22
	s_nop 1
	v_addc_co_u32_e32 v21, vcc, 0, v23, vcc
	global_load_dwordx4 v[20:23], v[20:21], off offset:768
	s_branch .LBB0_816

.LBB0_2043:
	s_ashr_i32 s2, s4, 31
	s_lshr_b32 s2, s2, 28
	s_add_i32 s2, s4, s2
	s_ashr_i32 s2, s2, 4
	s_lshl_b32 s3, s2, 10
	s_lshl_b32 s6, s4, 6
	s_lshl_b32 s5, s2, 6
	s_sub_i32 s6, s6, s3
	s_mul_i32 s2, s2, 0x58000
	v_readlane_b32 s7, v253, 3
	s_mul_hi_i32 s3, s5, 0x1600
	s_add_u32 s2, s7, s2
	v_readlane_b32 s7, v253, 4
	s_addc_u32 s3, s7, s3
	s_mul_i32 s8, s6, 0x1600
	v_readlane_b32 s10, v254, 5
	s_mul_hi_i32 s7, s6, 0x1600
	v_readlane_b32 s11, v254, 6
	s_add_u32 s8, s10, s8
	v_lshl_add_u64 v[0:1], s[2:3], 0, v[128:129]
	v_mov_b32_e32 v89, v129
	s_addc_u32 s9, s11, s7
	v_mov_b32_e32 v87, v129
	v_lshl_add_u64 v[4:5], v[0:1], 0, v[88:89]
	s_mov_b32 s7, 0x16000
	v_lshl_add_u64 v[2:3], s[8:9], 0, v[86:87]
	v_add_co_u32_e32 v6, vcc, s7, v4
	v_lshl_add_u64 v[2:3], v[2:3], 0, v[128:129]
	s_nop 0
	v_addc_co_u32_e32 v7, vcc, 0, v5, vcc
	s_mov_b32 s10, 0x2c000
	global_load_dwordx4 v[20:23], v[2:3], off offset:256
	s_nop 0
	global_load_dwordx4 v[0:3], v[4:5], off
	global_load_dwordx4 v[8:11], v[6:7], off
	v_add_co_u32_e32 v6, vcc, s10, v4
	s_mov_b32 s11, 0x42000
	s_nop 0
	v_addc_co_u32_e32 v7, vcc, 0, v5, vcc
	v_add_co_u32_e32 v4, vcc, s11, v4
	v_mov_b32_e32 v91, v129
	s_nop 0
	v_addc_co_u32_e32 v5, vcc, 0, v5, vcc
	global_load_dwordx4 v[16:19], v[6:7], off
	global_load_dwordx4 v[32:35], v[4:5], off
	v_lshl_add_u64 v[4:5], s[2:3], 0, v[88:89]
	v_lshl_add_u64 v[24:25], v[4:5], 0, v[128:129]
	v_add_co_u32_e32 v12, vcc, s7, v24
	v_mov_b32_e32 v93, v129
	s_nop 0
	v_addc_co_u32_e32 v13, vcc, 0, v25, vcc
	v_add_co_u32_e32 v26, vcc, s10, v24
	global_load_dwordx4 v[4:7], v[24:25], off offset:256
	s_nop 0
	global_load_dwordx4 v[12:15], v[12:13], off offset:256
	v_addc_co_u32_e32 v27, vcc, 0, v25, vcc
	v_add_co_u32_e32 v24, vcc, s11, v24
	v_lshl_add_u64 v[40:41], s[8:9], 0, v[128:129]
	s_nop 0
	v_addc_co_u32_e32 v25, vcc, 0, v25, vcc
	global_load_dwordx4 v[28:31], v[26:27], off offset:256
	global_load_dwordx4 v[48:51], v[24:25], off offset:256
	v_lshl_add_u64 v[24:25], s[8:9], 0, v[90:91]
	v_lshl_add_u64 v[24:25], v[24:25], 0, v[128:129]
	v_lshl_add_u64 v[26:27], s[8:9], 0, v[92:93]
	v_add_co_u32_e32 v54, vcc, s7, v24
	v_lshl_add_u64 v[42:43], v[26:27], 0, v[128:129]
	s_nop 0
	v_addc_co_u32_e32 v55, vcc, 0, v25, vcc
	global_load_dwordx4 v[44:47], v[24:25], off offset:256
	global_load_dwordx4 v[36:39], v[42:43], off offset:256
	v_lshl_add_u64 v[26:27], s[8:9], 0, v[88:89]
	v_add_co_u32_e32 v42, vcc, s7, v42
	v_lshl_add_u64 v[52:53], v[26:27], 0, v[128:129]
	s_nop 0
	v_addc_co_u32_e32 v43, vcc, 0, v43, vcc
	global_load_dwordx4 v[24:27], v[52:53], off offset:256
	global_load_dwordx4 v[60:63], v[54:55], off
	v_add_co_u32_e32 v52, vcc, s7, v52
	v_lshl_add_u64 v[40:41], v[40:41], 0, v[88:89]
	s_nop 0
	v_addc_co_u32_e32 v53, vcc, 0, v53, vcc
	global_load_dwordx4 v[56:59], v[42:43], off
	s_nop 0
	global_load_dwordx4 v[52:55], v[52:53], off
	v_mov_b32_e32 v64, 0
	global_load_dwordx4 v[40:43], v[40:41], off
	v_mad_i64_i32 v[94:95], s[2:3], s6, v190, v[82:83]
	v_mad_i64_i32 v[96:97], s[2:3], s5, v190, v[84:85]
	s_mov_b32 s7, -2
	v_mov_b32_e32 v65, v64
	v_mov_b32_e32 v66, v64
	v_mov_b32_e32 v67, v64
	v_mov_b32_e32 v68, v64
	v_mov_b32_e32 v69, v64
	v_mov_b32_e32 v70, v64
	v_mov_b32_e32 v71, v64
	v_mov_b32_e32 v72, v64
	v_mov_b32_e32 v73, v64
	v_mov_b32_e32 v74, v64
	v_mov_b32_e32 v75, v64
	v_mov_b32_e32 v76, v64
	v_mov_b32_e32 v77, v64
	v_mov_b32_e32 v78, v64
	v_mov_b32_e32 v79, v64
	s_mov_b64 s[8:9], 0x200
	s_waitcnt vmcnt(0)
	s_branch .LBB0_2045

.LBB0_2045:
	s_add_i32 s7, s7, 2
	s_cmp_gt_u32 s7, 19
	s_cselect_b64 s[2:3], -1, 0
	s_and_b64 vcc, exec, s[2:3]
	v_lshl_add_u64 v[100:101], v[96:97], 0, v[80:81]
	v_lshl_add_u64 v[98:99], v[94:95], 0, v[80:81]
	s_waitcnt lgkmcnt(0)
	s_barrier
	s_waitcnt vmcnt(8)
	ds_write_b128 v104, v[0:3]
	ds_write_b128 v104, v[40:43] offset:17408
	ds_write_b128 v105, v[8:11]
	ds_write_b128 v105, v[52:55] offset:17408
	ds_write_b128 v106, v[16:19]
	ds_write_b128 v106, v[56:59] offset:17408
	ds_write_b128 v107, v[32:35]
	ds_write_b128 v107, v[60:63] offset:17408
	s_waitcnt lgkmcnt(0)
	s_barrier
	s_cbranch_vccnz .LBB0_2047
	v_add_co_u32_e32 v0, vcc, 0xb000000, v100
	s_nop 1
	v_addc_co_u32_e32 v1, vcc, 0, v101, vcc
	v_add_co_u32_e32 v8, vcc, 0x2350000, v98
	global_load_dwordx4 v[0:3], v[0:1], off offset:512
	s_nop 0
	v_addc_co_u32_e32 v9, vcc, 0, v99, vcc
	global_load_dwordx4 v[40:43], v[8:9], off offset:512
	v_add_co_u32_e32 v8, vcc, 0xb016000, v100
	s_nop 1
	v_addc_co_u32_e32 v9, vcc, 0, v101, vcc
	v_add_co_u32_e32 v16, vcc, 0x2366000, v98
	global_load_dwordx4 v[8:11], v[8:9], off offset:512
	s_nop 0
	v_addc_co_u32_e32 v17, vcc, 0, v99, vcc
	global_load_dwordx4 v[52:55], v[16:17], off offset:512
	v_add_co_u32_e32 v16, vcc, 0xb02c000, v100
	s_nop 1
	v_addc_co_u32_e32 v17, vcc, 0, v101, vcc
	v_add_co_u32_e32 v32, vcc, 0x237c000, v98
	global_load_dwordx4 v[16:19], v[16:17], off offset:512
	s_nop 0
	v_addc_co_u32_e32 v33, vcc, 0, v99, vcc
	global_load_dwordx4 v[56:59], v[32:33], off offset:512
	v_add_co_u32_e32 v32, vcc, 0xb042000, v100
	s_nop 1
	v_addc_co_u32_e32 v33, vcc, 0, v101, vcc
	v_add_co_u32_e32 v60, vcc, 0x2392000, v98
	global_load_dwordx4 v[32:35], v[32:33], off offset:512
	s_nop 0
	v_addc_co_u32_e32 v61, vcc, 0, v99, vcc
	global_load_dwordx4 v[60:63], v[60:61], off offset:512
.LBB0_2047:
	ds_read_b128 v[110:113], v108
	ds_read_b128 v[114:117], v108 offset:4352
	ds_read_b128 v[118:121], v109 offset:17408
	ds_read_b128 v[122:125], v109 offset:21760
	s_cmp_gt_u32 s7, 18
	s_waitcnt lgkmcnt(1)
	v_mfma_f32_16x16x32_bf16 v[76:79], v[118:121], v[110:113], v[76:79]
	s_waitcnt lgkmcnt(0)
	v_mfma_f32_16x16x32_bf16 v[72:75], v[122:125], v[110:113], v[72:75]
	v_mfma_f32_16x16x32_bf16 v[68:71], v[118:121], v[114:117], v[68:71]
	v_mfma_f32_16x16x32_bf16 v[64:67], v[122:125], v[114:117], v[64:67]
	ds_read_b128 v[110:113], v108 offset:64
	ds_read_b128 v[114:117], v108 offset:4416
	ds_read_b128 v[118:121], v109 offset:17472
	ds_read_b128 v[122:125], v109 offset:21824
	s_waitcnt lgkmcnt(1)
	v_mfma_f32_16x16x32_bf16 v[76:79], v[118:121], v[110:113], v[76:79]
	s_waitcnt lgkmcnt(0)
	v_mfma_f32_16x16x32_bf16 v[72:75], v[122:125], v[110:113], v[72:75]
	v_mfma_f32_16x16x32_bf16 v[68:71], v[118:121], v[114:117], v[68:71]
	v_mfma_f32_16x16x32_bf16 v[64:67], v[122:125], v[114:117], v[64:67]
	ds_read_b128 v[110:113], v108 offset:128
	ds_read_b128 v[114:117], v108 offset:4480
	ds_read_b128 v[118:121], v109 offset:17536
	ds_read_b128 v[122:125], v109 offset:21888
	s_waitcnt lgkmcnt(1)
	v_mfma_f32_16x16x32_bf16 v[76:79], v[118:121], v[110:113], v[76:79]
	s_waitcnt lgkmcnt(0)
	v_mfma_f32_16x16x32_bf16 v[72:75], v[122:125], v[110:113], v[72:75]
	v_mfma_f32_16x16x32_bf16 v[68:71], v[118:121], v[114:117], v[68:71]
	v_mfma_f32_16x16x32_bf16 v[64:67], v[122:125], v[114:117], v[64:67]
	ds_read_b128 v[110:113], v108 offset:192
	ds_read_b128 v[114:117], v108 offset:4544
	ds_read_b128 v[118:121], v109 offset:17600
	ds_read_b128 v[122:125], v109 offset:21952
	s_waitcnt lgkmcnt(0)
	s_barrier
	v_mfma_f32_16x16x32_bf16 v[76:79], v[118:121], v[110:113], v[76:79]
	s_waitcnt vmcnt(8)
	s_cbranch_scc0 .Lg64w1
	s_waitcnt vmcnt(0)
.Lg64w1:
	ds_write_b128 v104, v[4:7]
	ds_write_b128 v104, v[24:27] offset:17408
	ds_write_b128 v105, v[12:15]
	ds_write_b128 v105, v[36:39] offset:17408
	ds_write_b128 v106, v[28:31]
	ds_write_b128 v106, v[44:47] offset:17408
	ds_write_b128 v107, v[48:51]
	ds_write_b128 v107, v[20:23] offset:17408
	s_waitcnt lgkmcnt(0)
	v_mfma_f32_16x16x32_bf16 v[72:75], v[122:125], v[110:113], v[72:75]
	s_barrier
	v_mfma_f32_16x16x32_bf16 v[68:71], v[118:121], v[114:117], v[68:71]
	v_mfma_f32_16x16x32_bf16 v[64:67], v[122:125], v[114:117], v[64:67]
	s_cbranch_scc1 .LBB0_2044
	v_add_co_u32_e32 v4, vcc, 0xb000000, v100
	s_nop 1
	v_addc_co_u32_e32 v5, vcc, 0, v101, vcc
	v_add_co_u32_e32 v12, vcc, 0x2350000, v98
	global_load_dwordx4 v[4:7], v[4:5], off offset:768
	s_nop 0
	v_addc_co_u32_e32 v13, vcc, 0, v99, vcc
	global_load_dwordx4 v[24:27], v[12:13], off offset:768
	v_add_co_u32_e32 v12, vcc, 0xb016000, v100
	s_nop 1
	v_addc_co_u32_e32 v13, vcc, 0, v101, vcc
	v_add_co_u32_e32 v20, vcc, 0x2366000, v98
	global_load_dwordx4 v[12:15], v[12:13], off offset:768
	s_nop 0
	v_addc_co_u32_e32 v21, vcc, 0, v99, vcc
	global_load_dwordx4 v[36:39], v[20:21], off offset:768
	v_add_co_u32_e32 v20, vcc, 0xb02c000, v100
	s_nop 1
	v_addc_co_u32_e32 v21, vcc, 0, v101, vcc
	global_load_dwordx4 v[28:31], v[20:21], off offset:768
	v_add_co_u32_e32 v20, vcc, 0x237c000, v98
	s_nop 1
	v_addc_co_u32_e32 v21, vcc, 0, v99, vcc
	global_load_dwordx4 v[44:47], v[20:21], off offset:768
	v_add_co_u32_e32 v20, vcc, 0xb042000, v100
	s_nop 1
	v_addc_co_u32_e32 v21, vcc, 0, v101, vcc
	global_load_dwordx4 v[48:51], v[20:21], off offset:768
	v_add_co_u32_e32 v20, vcc, 0x2392000, v98
	s_nop 1
	v_addc_co_u32_e32 v21, vcc, 0, v99, vcc
	global_load_dwordx4 v[20:23], v[20:21], off offset:768
	s_branch .LBB0_2044
